# global attention inner loop rewritten by hand (3-slot LDS ring, prefetch distance 2, half-iteration stagger between wave halves, LDS fragment reads one phase ahead, in-place exp) + NA bias table fille
# baseline (speedup 1.0000x reference)
.LBB0_732:
	s_lshr_b32 s6, s19, 5
	s_lshl_b32 s44, s6, 11
	s_bfe_u32 s25, s19, 0x10004
	s_lshl_b32 s6, s6, 1
	s_or_b32 s6, s6, s25
	s_lshl_b64 s[42:43], s[6:7], 18
	s_sub_i32 s6, 0x3ff, s24
	s_lshl_b32 s30, s6, 9
	v_mbcnt_lo_u32_b32 v34, -1, 0
	v_mbcnt_hi_u32_b32 v34, -1, v34
	s_lshr_b32 s26, s6, 5
	v_add_u32_e32 v18, s33, v34
	v_and_b32_e32 v35, 31, v34
	s_and_b32 s30, s30, 0x600
	s_lshl_b32 s28, s25, 7
	v_readfirstlane_b32 s25, v18
	s_lshl_b32 s27, s26, 11
	v_or_b32_e32 v16, s30, v35
	s_andn2_b32 s25, s25, 63
	v_or_b32_e32 v16, s27, v16
	s_bfe_u32 s29, s6, 0x10004
	v_add_u32_e32 v200, s25, v16
	s_lshl_b32 s6, s6, 4
	v_ashrrev_i32_e32 v201, 31, v200
	s_lshl_b32 s25, s29, 8
	s_and_b32 s6, s6, 0xc0
	v_lshlrev_b64 v[16:17], 10, v[200:201]
	s_or_b32 s25, s25, s6
	v_lshl_add_u64 v[16:17], s[88:89], 0, v[16:17]
	s_lshl_b32 s6, s25, 1
	v_lshl_add_u64 v[26:27], v[16:17], 0, s[6:7]
	v_ashrrev_i32_e32 v28, 3, v18
	s_lshl_b32 s6, s26, 1
	v_add_u32_e32 v16, s27, v28
	s_or_b32 s6, s6, s29
	s_ashr_i32 s45, s44, 31
	v_ashrrev_i32_e32 v17, 31, v16
	s_lshl_b64 s[26:27], s[6:7], 18
	v_readlane_b32 s6, v254, 49
	v_lshlrev_b64 v[16:17], 8, v[16:17]
	v_ashrrev_i32_e32 v29, 31, v28
	s_add_u32 s26, s6, s26
	v_readlane_b32 s6, v254, 50
	s_addc_u32 s27, s6, s27
	v_lshlrev_b64 v[30:31], 12, v[28:29]
	v_lshl_add_u64 v[16:17], s[10:11], 0, v[16:17]
	s_lshl_b32 s6, s29, 7
	v_lshlrev_b32_e32 v20, 4, v34
	v_bfe_u32 v145, v34, 5, 1
	v_lshl_add_u64 v[18:19], s[26:27], 0, v[30:31]
	v_lshl_add_u64 v[16:17], v[16:17], 0, s[6:7]
	v_and_b32_e32 v32, 0x70, v20
	v_mov_b32_e32 v33, v144
	v_mov_b32_e32 v205, v144
	v_lshlrev_b32_e32 v204, 4, v145
	v_lshl_add_u64 v[16:17], v[16:17], 0, v[32:33]
	v_lshl_add_u64 v[22:23], v[18:19], 0, v[32:33]
	v_lshl_add_u64 v[26:27], v[26:27], 0, v[204:205]
	s_mov_b32 s26, 0x8000
	global_load_dwordx4 v[18:21], v[16:17], off
	s_nop 0
	global_load_dwordx4 v[22:25], v[22:23], off
	s_nop 0
	global_load_dwordx4 v[170:173], v[26:27], off
	global_load_dwordx4 v[158:161], v[26:27], off offset:32
	global_load_dwordx4 v[154:157], v[26:27], off offset:64
	global_load_dwordx4 v[146:149], v[26:27], off offset:96
	v_add_co_u32_e32 v26, vcc, s26, v26
	v_lshlrev_b32_e32 v17, 1, v34
	s_nop 0
	v_addc_co_u32_e32 v27, vcc, 0, v27, vcc
	global_load_dwordx4 v[174:177], v[26:27], off
	global_load_dwordx4 v[166:169], v[26:27], off offset:32
	global_load_dwordx4 v[162:165], v[26:27], off offset:64
	global_load_dwordx4 v[150:153], v[26:27], off offset:96
	v_lshrrev_b32_e32 v33, 1, v34
	v_and_b32_e32 v34, 19, v34
	v_and_b32_e32 v17, 8, v17
	v_and_b32_e32 v33, 4, v33
	v_or3_b32 v17, v17, v34, v33
	v_mul_lo_u32 v33, v28, s31
	v_lshl_add_u64 v[28:29], v[28:29], 0, s[44:45]
	v_lshlrev_b64 v[26:27], 8, v[28:29]
	v_readlane_b32 s26, v253, 44
	v_or3_b32 v26, v26, s28, v32
	v_readlane_b32 s27, v253, 45
	v_lshl_add_u64 v[28:29], s[42:43], 0, v[30:31]
	v_mov_b32_e32 v16, 0
	v_lshl_add_u64 v[206:207], s[26:27], 0, v[26:27]
	v_readlane_b32 s26, v253, 47
	v_add3_u32 v222, 0, v33, v32
	v_or_b32_e32 v28, v28, v32
	v_readlane_b32 s27, v253, 48
	s_mov_b32 s6, 1
	v_mul_u32_u24_e32 v220, 0x90, v35
	v_mul_u32_u24_e32 v221, 0x90, v17
	v_lshl_add_u64 v[208:209], s[26:27], 0, v[28:29]
	global_load_dwordx4 v[182:185], v[206:207], off
	global_load_dwordx4 v[178:181], v[208:209], off
	s_mov_b64 s[26:27], 0x4000
	v_lshl_add_u64 v[206:207], v[206:207], 0, s[26:27]
	v_lshl_add_u64 v[208:209], v[208:209], 0, s[0:1]
	s_barrier
	v_mov_b32_e32 v17, v16
	v_mov_b32_e32 v26, v16
	v_mov_b32_e32 v27, v16
	v_mov_b32_e32 v28, v16
	v_mov_b32_e32 v29, v16
	v_mov_b32_e32 v30, v16
	v_mov_b32_e32 v31, v16
	v_mov_b32_e32 v32, v16
	s_waitcnt vmcnt(11)
	ds_write_b128 v222, v[18:21]
	s_waitcnt vmcnt(10)
	ds_write_b128 v222, v[22:25] offset:9216
	v_mov_b32_e32 v18, v16
	v_mov_b32_e32 v19, v16
	v_mov_b32_e32 v20, v16
	v_mov_b32_e32 v21, v16
	v_mov_b32_e32 v22, v16
	v_mov_b32_e32 v23, v16
	v_mov_b32_e32 v24, v16
	v_mov_b32_e32 v25, v16
	v_mov_b32_e32 v33, v16
	v_mov_b32_e32 v34, v16
	v_mov_b32_e32 v35, v16
	v_mov_b32_e32 v36, v16
	v_mov_b32_e32 v37, v16
	v_mov_b32_e32 v38, v16
	v_mov_b32_e32 v39, v16
	v_mov_b32_e32 v40, v16
	v_mov_b32_e32 v41, v16
	v_mov_b32_e32 v42, v16
	v_mov_b32_e32 v43, v16
	v_mov_b32_e32 v44, v16
	v_mov_b32_e32 v45, v16
	v_mov_b32_e32 v46, v16
	v_mov_b32_e32 v47, v16
	v_mov_b32_e32 v48, v16
	v_mov_b32_e32 v49, v16
	v_mov_b32_e32 v50, v16
	v_mov_b32_e32 v51, v16
	v_mov_b32_e32 v52, v16
	v_mov_b32_e32 v53, v16
	v_mov_b32_e32 v54, v16
	v_mov_b32_e32 v55, v16
	v_mov_b32_e32 v56, v16
	v_mov_b32_e32 v57, v16
	v_mov_b32_e32 v58, v16
	v_mov_b32_e32 v59, v16
	v_mov_b32_e32 v60, v16
	v_mov_b32_e32 v61, v16
	v_mov_b32_e32 v62, v16
	v_mov_b32_e32 v63, v16
	v_mov_b32_e32 v64, v16
	v_mov_b32_e32 v65, v16
	v_mov_b32_e32 v66, v16
	v_mov_b32_e32 v67, v16
	v_mov_b32_e32 v68, v16
	v_mov_b32_e32 v69, v16
	v_mov_b32_e32 v70, v16
	v_mov_b32_e32 v71, v16
	v_mov_b32_e32 v72, v16
	v_mov_b32_e32 v73, v16
	v_mov_b32_e32 v74, v16
	v_mov_b32_e32 v75, v16
	v_mov_b32_e32 v76, v16
	v_mov_b32_e32 v77, v16
	v_mov_b32_e32 v78, v16
	v_mov_b32_e32 v79, v16
	v_mov_b32_e32 v202, v16
	v_mov_b32_e32 v203, v16
	s_waitcnt lgkmcnt(0)
	s_barrier
	v_mov_b32_e32 v186, 0
	v_mov_b32_e32 v187, 0
	v_mov_b32_e32 v188, 0
	v_mov_b32_e32 v189, 0
	v_add3_u32 v190, 0, v221, v204
	ds_read_b128 v[224:227], v190
	ds_read_b128 v[228:231], v190 offset:4608
	ds_read_b128 v[232:235], v190 offset:32
	ds_read_b128 v[236:239], v190 offset:4640
	ds_read_b128 v[240:243], v190 offset:64
	ds_read_b128 v[244:247], v190 offset:4672
	ds_read_b128 v[248:251], v190 offset:96
	ds_read_b128 v[192:195], v190 offset:4704
	s_waitcnt vmcnt(0)
	ds_write_b128 v222, v[182:185] offset:18432
	ds_write_b128 v222, v[178:181] offset:27648
	s_mov_b32 s100, 0
	s_mov_b32 s101, 0x4800
	s_mov_b32 s26, 0x9000
	s_mov_b32 s6, 0
	s_mov_b64 s[28:29], 0x4000
.Lag_loop:
	v_add3_u32 v191, s100, v220, v204
	v_add3_u32 v190, s101, v221, v204
	v_add_u32_e32 v196, s26, v222
	s_waitcnt lgkmcnt(9)
	v_mfma_f32_32x32x16_bf16 v[112:127], v[224:227], v[170:173], v[0:15]
	v_mfma_f32_32x32x16_bf16 v[80:95], v[224:227], v[174:177], v[0:15]
	ds_read_b128 v[224:227], v191 offset:9216
	s_waitcnt lgkmcnt(9)
	v_mfma_f32_32x32x16_bf16 v[128:143], v[228:231], v[170:173], v[0:15]
	v_mfma_f32_32x32x16_bf16 v[96:111], v[228:231], v[174:177], v[0:15]
	ds_read_b128 v[228:231], v191 offset:13824
	s_waitcnt lgkmcnt(9)
	v_mfma_f32_32x32x16_bf16 v[112:127], v[232:235], v[158:161], v[112:127]
	v_mfma_f32_32x32x16_bf16 v[80:95], v[232:235], v[166:169], v[80:95]
	ds_read_b128 v[232:235], v191 offset:9248
	s_waitcnt lgkmcnt(9)
	v_mfma_f32_32x32x16_bf16 v[128:143], v[236:239], v[158:161], v[128:143]
	v_mfma_f32_32x32x16_bf16 v[96:111], v[236:239], v[166:169], v[96:111]
	ds_read_b128 v[236:239], v191 offset:13856
	s_waitcnt lgkmcnt(9)
	v_mfma_f32_32x32x16_bf16 v[112:127], v[240:243], v[154:157], v[112:127]
	v_mfma_f32_32x32x16_bf16 v[80:95], v[240:243], v[162:165], v[80:95]
	ds_read_b128 v[240:243], v191 offset:9280
	s_waitcnt lgkmcnt(9)
	v_mfma_f32_32x32x16_bf16 v[128:143], v[244:247], v[154:157], v[128:143]
	v_mfma_f32_32x32x16_bf16 v[96:111], v[244:247], v[162:165], v[96:111]
	ds_read_b128 v[244:247], v191 offset:13888
	s_waitcnt lgkmcnt(9)
	v_mfma_f32_32x32x16_bf16 v[112:127], v[248:251], v[146:149], v[112:127]
	v_mfma_f32_32x32x16_bf16 v[80:95], v[248:251], v[150:153], v[80:95]
	ds_read_b128 v[248:251], v191 offset:9312
	s_waitcnt lgkmcnt(9)
	v_mfma_f32_32x32x16_bf16 v[128:143], v[192:195], v[146:149], v[128:143]
	v_mfma_f32_32x32x16_bf16 v[96:111], v[192:195], v[150:153], v[96:111]
	ds_read_b128 v[192:195], v191 offset:13920
	global_load_dwordx4 v[182:185], v[206:207], off
	global_load_dwordx4 v[178:181], v[208:209], off
	v_lshl_add_u64 v[206:207], v[206:207], 0, s[28:29]
	v_lshl_add_u64 v[208:209], v[208:209], 0, s[0:1]
	s_cmp_lt_u32 s33, 0x100
	s_cbranch_scc1 .Lag_nobar_b
	s_barrier
.Lag_nobar_b:
	s_nop 7
	s_nop 1
	v_exp_f32_e32 v112, v112
	v_exp_f32_e32 v113, v113
	v_exp_f32_e32 v114, v114
	v_exp_f32_e32 v115, v115
	v_exp_f32_e32 v116, v116
	v_exp_f32_e32 v117, v117
	v_exp_f32_e32 v118, v118
	v_exp_f32_e32 v119, v119
	v_exp_f32_e32 v120, v120
	v_exp_f32_e32 v121, v121
	v_exp_f32_e32 v122, v122
	v_exp_f32_e32 v123, v123
	v_exp_f32_e32 v124, v124
	v_exp_f32_e32 v125, v125
	v_exp_f32_e32 v126, v126
	v_exp_f32_e32 v127, v127
	v_exp_f32_e32 v80, v80
	v_exp_f32_e32 v81, v81
	v_exp_f32_e32 v82, v82
	v_exp_f32_e32 v83, v83
	v_exp_f32_e32 v84, v84
	v_exp_f32_e32 v85, v85
	v_exp_f32_e32 v86, v86
	v_exp_f32_e32 v87, v87
	v_exp_f32_e32 v88, v88
	v_exp_f32_e32 v89, v89
	v_exp_f32_e32 v90, v90
	v_exp_f32_e32 v91, v91
	v_exp_f32_e32 v92, v92
	v_exp_f32_e32 v93, v93
	v_exp_f32_e32 v94, v94
	v_exp_f32_e32 v95, v95
	v_pk_add_f32 v[186:187], v[186:187], v[112:113]
	v_cvt_pk_bf16_f32 v112, v112, v113
	v_pk_add_f32 v[186:187], v[186:187], v[114:115]
	v_cvt_pk_bf16_f32 v113, v114, v115
	v_pk_add_f32 v[186:187], v[186:187], v[116:117]
	v_cvt_pk_bf16_f32 v114, v116, v117
	v_pk_add_f32 v[186:187], v[186:187], v[118:119]
	v_cvt_pk_bf16_f32 v115, v118, v119
	v_pk_add_f32 v[186:187], v[186:187], v[120:121]
	v_cvt_pk_bf16_f32 v116, v120, v121
	v_pk_add_f32 v[186:187], v[186:187], v[122:123]
	v_cvt_pk_bf16_f32 v117, v122, v123
	v_pk_add_f32 v[186:187], v[186:187], v[124:125]
	v_cvt_pk_bf16_f32 v118, v124, v125
	v_pk_add_f32 v[186:187], v[186:187], v[126:127]
	v_cvt_pk_bf16_f32 v119, v126, v127
	v_exp_f32_e32 v128, v128
	v_exp_f32_e32 v129, v129
	v_exp_f32_e32 v130, v130
	v_exp_f32_e32 v131, v131
	v_exp_f32_e32 v132, v132
	v_exp_f32_e32 v133, v133
	v_exp_f32_e32 v134, v134
	v_exp_f32_e32 v135, v135
	v_exp_f32_e32 v136, v136
	v_exp_f32_e32 v137, v137
	v_exp_f32_e32 v138, v138
	v_exp_f32_e32 v139, v139
	v_exp_f32_e32 v140, v140
	v_exp_f32_e32 v141, v141
	v_exp_f32_e32 v142, v142
	v_exp_f32_e32 v143, v143
	v_pk_add_f32 v[188:189], v[188:189], v[80:81]
	v_cvt_pk_bf16_f32 v80, v80, v81
	v_pk_add_f32 v[188:189], v[188:189], v[82:83]
	v_cvt_pk_bf16_f32 v81, v82, v83
	v_pk_add_f32 v[188:189], v[188:189], v[84:85]
	v_cvt_pk_bf16_f32 v82, v84, v85
	v_pk_add_f32 v[188:189], v[188:189], v[86:87]
	v_cvt_pk_bf16_f32 v83, v86, v87
	v_pk_add_f32 v[188:189], v[188:189], v[88:89]
	v_cvt_pk_bf16_f32 v84, v88, v89
	v_pk_add_f32 v[188:189], v[188:189], v[90:91]
	v_cvt_pk_bf16_f32 v85, v90, v91
	v_pk_add_f32 v[188:189], v[188:189], v[92:93]
	v_cvt_pk_bf16_f32 v86, v92, v93
	v_pk_add_f32 v[188:189], v[188:189], v[94:95]
	v_cvt_pk_bf16_f32 v87, v94, v95
	v_exp_f32_e32 v96, v96
	v_exp_f32_e32 v97, v97
	v_exp_f32_e32 v98, v98
	v_exp_f32_e32 v99, v99
	v_exp_f32_e32 v100, v100
	v_exp_f32_e32 v101, v101
	v_exp_f32_e32 v102, v102
	v_exp_f32_e32 v103, v103
	v_exp_f32_e32 v104, v104
	v_exp_f32_e32 v105, v105
	v_exp_f32_e32 v106, v106
	v_exp_f32_e32 v107, v107
	v_exp_f32_e32 v108, v108
	v_exp_f32_e32 v109, v109
	v_exp_f32_e32 v110, v110
	v_exp_f32_e32 v111, v111
	v_pk_add_f32 v[186:187], v[186:187], v[128:129]
	v_cvt_pk_bf16_f32 v128, v128, v129
	v_pk_add_f32 v[186:187], v[186:187], v[130:131]
	v_cvt_pk_bf16_f32 v129, v130, v131
	v_pk_add_f32 v[186:187], v[186:187], v[132:133]
	v_cvt_pk_bf16_f32 v130, v132, v133
	v_pk_add_f32 v[186:187], v[186:187], v[134:135]
	v_cvt_pk_bf16_f32 v131, v134, v135
	v_pk_add_f32 v[186:187], v[186:187], v[136:137]
	v_cvt_pk_bf16_f32 v132, v136, v137
	v_pk_add_f32 v[186:187], v[186:187], v[138:139]
	v_cvt_pk_bf16_f32 v133, v138, v139
	v_pk_add_f32 v[186:187], v[186:187], v[140:141]
	v_cvt_pk_bf16_f32 v134, v140, v141
	v_pk_add_f32 v[186:187], v[186:187], v[142:143]
	v_cvt_pk_bf16_f32 v135, v142, v143
	v_pk_add_f32 v[188:189], v[188:189], v[96:97]
	v_cvt_pk_bf16_f32 v96, v96, v97
	v_pk_add_f32 v[188:189], v[188:189], v[98:99]
	v_cvt_pk_bf16_f32 v97, v98, v99
	v_pk_add_f32 v[188:189], v[188:189], v[100:101]
	v_cvt_pk_bf16_f32 v98, v100, v101
	v_pk_add_f32 v[188:189], v[188:189], v[102:103]
	v_cvt_pk_bf16_f32 v99, v102, v103
	v_pk_add_f32 v[188:189], v[188:189], v[104:105]
	v_cvt_pk_bf16_f32 v100, v104, v105
	v_pk_add_f32 v[188:189], v[188:189], v[106:107]
	v_cvt_pk_bf16_f32 v101, v106, v107
	v_pk_add_f32 v[188:189], v[188:189], v[108:109]
	v_cvt_pk_bf16_f32 v102, v108, v109
	v_pk_add_f32 v[188:189], v[188:189], v[110:111]
	v_cvt_pk_bf16_f32 v103, v110, v111
	s_cmp_lt_u32 s33, 0x100
	s_cbranch_scc0 .Lag_nobar_a
	s_barrier
.Lag_nobar_a:
	s_nop 1
	s_waitcnt lgkmcnt(7)
	v_mfma_f32_32x32x16_bf16 v[64:79], v[224:227], v[112:115], v[64:79]
	v_mfma_f32_32x32x16_bf16 v[32:47], v[224:227], v[80:83], v[32:47]
	ds_read_b128 v[224:227], v190
	s_waitcnt lgkmcnt(7)
	v_mfma_f32_32x32x16_bf16 v[48:63], v[228:231], v[112:115], v[48:63]
	v_mfma_f32_32x32x16_bf16 v[16:31], v[228:231], v[80:83], v[16:31]
	ds_read_b128 v[228:231], v190 offset:4608
	s_waitcnt lgkmcnt(7)
	v_mfma_f32_32x32x16_bf16 v[64:79], v[232:235], v[116:119], v[64:79]
	v_mfma_f32_32x32x16_bf16 v[32:47], v[232:235], v[84:87], v[32:47]
	ds_read_b128 v[232:235], v190 offset:32
	s_waitcnt lgkmcnt(7)
	v_mfma_f32_32x32x16_bf16 v[48:63], v[236:239], v[116:119], v[48:63]
	v_mfma_f32_32x32x16_bf16 v[16:31], v[236:239], v[84:87], v[16:31]
	ds_read_b128 v[236:239], v190 offset:4640
	s_waitcnt lgkmcnt(7)
	v_mfma_f32_32x32x16_bf16 v[64:79], v[240:243], v[128:131], v[64:79]
	v_mfma_f32_32x32x16_bf16 v[32:47], v[240:243], v[96:99], v[32:47]
	ds_read_b128 v[240:243], v190 offset:64
	s_waitcnt lgkmcnt(7)
	v_mfma_f32_32x32x16_bf16 v[48:63], v[244:247], v[128:131], v[48:63]
	v_mfma_f32_32x32x16_bf16 v[16:31], v[244:247], v[96:99], v[16:31]
	ds_read_b128 v[244:247], v190 offset:4672
	s_waitcnt lgkmcnt(7)
	v_mfma_f32_32x32x16_bf16 v[64:79], v[248:251], v[132:135], v[64:79]
	v_mfma_f32_32x32x16_bf16 v[32:47], v[248:251], v[100:103], v[32:47]
	ds_read_b128 v[248:251], v190 offset:96
	s_waitcnt lgkmcnt(7)
	v_mfma_f32_32x32x16_bf16 v[48:63], v[192:195], v[132:135], v[48:63]
	v_mfma_f32_32x32x16_bf16 v[16:31], v[192:195], v[100:103], v[16:31]
	ds_read_b128 v[192:195], v190 offset:4704
	s_waitcnt vmcnt(0)
	ds_write_b128 v196, v[182:185]
	ds_write_b128 v196, v[178:181] offset:9216
	s_mov_b32 s27, s100
	s_mov_b32 s100, s101
	s_mov_b32 s101, s26
	s_mov_b32 s26, s27
	s_add_i32 s6, s6, 1
	s_cmp_lt_u32 s6, 32
	s_cbranch_scc1 .Lag_loop
	v_add_f32_e32 v82, v186, v187
	v_add_f32_e32 v84, v188, v189
	s_lshl_b32 s6, s25, 1
	s_add_u32 s26, s8, s6
	s_addc_u32 s27, s9, 0
	s_add_i32 s24, s24, s40
	s_sub_i32 s19, s19, s40
	s_cmpk_gt_i32 s24, 0x3ff
	ds_bpermute_b32 v83, v219, v82
	v_lshlrev_b32_e32 v80, 3, v145
	v_mov_b32_e32 v81, v144
	v_lshl_add_u64 v[80:81], s[26:27], 0, v[80:81]
	s_waitcnt lgkmcnt(0)
	v_add_f32_e32 v82, v82, v83
	v_rcp_f32_e32 v85, v82
	v_lshlrev_b64 v[82:83], 11, v[200:201]
	v_lshl_add_u64 v[82:83], v[80:81], 0, v[82:83]
	v_mul_f32_e32 v64, v64, v85
	v_mul_f32_e32 v65, v65, v85
	v_cvt_pk_bf16_f32 v64, v64, v65
	v_mul_f32_e32 v65, v66, v85
	v_mul_f32_e32 v48, v48, v85
	v_mul_f32_e32 v49, v49, v85
	v_mul_f32_e32 v66, v67, v85
	v_cvt_pk_bf16_f32 v65, v65, v66
	v_cvt_pk_bf16_f32 v48, v48, v49
	v_mul_f32_e32 v49, v50, v85
	v_mul_f32_e32 v50, v51, v85
	v_cvt_pk_bf16_f32 v49, v49, v50
	global_store_dwordx2 v[82:83], v[64:65], off
	global_store_dwordx2 v[82:83], v[48:49], off offset:64
	v_mul_f32_e32 v48, v68, v85
	v_mul_f32_e32 v49, v69, v85
	v_cvt_pk_bf16_f32 v48, v48, v49
	v_mul_f32_e32 v49, v70, v85
	v_mul_f32_e32 v50, v71, v85
	v_cvt_pk_bf16_f32 v49, v49, v50
	v_mul_f32_e32 v50, v52, v85
	v_mul_f32_e32 v51, v53, v85
	v_cvt_pk_bf16_f32 v50, v50, v51
	v_mul_f32_e32 v51, v54, v85
	v_mul_f32_e32 v52, v55, v85
	v_cvt_pk_bf16_f32 v51, v51, v52
	global_store_dwordx2 v[82:83], v[48:49], off offset:16
	global_store_dwordx2 v[82:83], v[50:51], off offset:80
	v_mul_f32_e32 v48, v72, v85
	v_mul_f32_e32 v49, v73, v85
	v_cvt_pk_bf16_f32 v48, v48, v49
	v_mul_f32_e32 v49, v74, v85
	v_mul_f32_e32 v50, v75, v85
	v_cvt_pk_bf16_f32 v49, v49, v50
	v_mul_f32_e32 v50, v56, v85
	v_mul_f32_e32 v51, v57, v85
	v_cvt_pk_bf16_f32 v50, v50, v51
	v_mul_f32_e32 v51, v58, v85
	v_mul_f32_e32 v52, v59, v85
	v_cvt_pk_bf16_f32 v51, v51, v52
	global_store_dwordx2 v[82:83], v[48:49], off offset:32
	global_store_dwordx2 v[82:83], v[50:51], off offset:96
	v_mul_f32_e32 v48, v76, v85
	v_mul_f32_e32 v49, v77, v85
	v_cvt_pk_bf16_f32 v48, v48, v49
	v_mul_f32_e32 v49, v78, v85
	v_mul_f32_e32 v50, v79, v85
	v_cvt_pk_bf16_f32 v49, v49, v50
	v_mul_f32_e32 v50, v60, v85
	v_mul_f32_e32 v51, v61, v85
	v_cvt_pk_bf16_f32 v50, v50, v51
	v_mul_f32_e32 v51, v62, v85
	v_mul_f32_e32 v52, v63, v85
	v_cvt_pk_bf16_f32 v51, v51, v52
	global_store_dwordx2 v[82:83], v[48:49], off offset:48
	global_store_dwordx2 v[82:83], v[50:51], off offset:112
	ds_bpermute_b32 v48, v219, v84
	s_waitcnt lgkmcnt(0)
	v_add_f32_e32 v48, v84, v48
	v_rcp_f32_e32 v50, v48
	v_or_b32_e32 v48, 32, v200
	v_ashrrev_i32_e32 v49, 31, v48
	v_lshlrev_b64 v[48:49], 11, v[48:49]
	v_mul_f32_e32 v32, v32, v50
	v_mul_f32_e32 v33, v33, v50
	v_cvt_pk_bf16_f32 v32, v32, v33
	v_mul_f32_e32 v33, v34, v50
	v_mul_f32_e32 v16, v16, v50
	v_mul_f32_e32 v17, v17, v50
	v_mul_f32_e32 v34, v35, v50
	v_cvt_pk_bf16_f32 v33, v33, v34
	v_cvt_pk_bf16_f32 v16, v16, v17
	v_mul_f32_e32 v17, v18, v50
	v_lshl_add_u64 v[48:49], v[80:81], 0, v[48:49]
	v_mul_f32_e32 v18, v19, v50
	v_cvt_pk_bf16_f32 v17, v17, v18
	global_store_dwordx2 v[48:49], v[32:33], off
	global_store_dwordx2 v[48:49], v[16:17], off offset:64
	v_mul_f32_e32 v16, v36, v50
	v_mul_f32_e32 v17, v37, v50
	v_cvt_pk_bf16_f32 v16, v16, v17
	v_mul_f32_e32 v17, v38, v50
	v_mul_f32_e32 v18, v39, v50
	v_cvt_pk_bf16_f32 v17, v17, v18
	v_mul_f32_e32 v18, v20, v50
	v_mul_f32_e32 v19, v21, v50
	v_cvt_pk_bf16_f32 v18, v18, v19
	v_mul_f32_e32 v19, v22, v50
	v_mul_f32_e32 v20, v23, v50
	v_cvt_pk_bf16_f32 v19, v19, v20
	global_store_dwordx2 v[48:49], v[16:17], off offset:16
	global_store_dwordx2 v[48:49], v[18:19], off offset:80
	v_mul_f32_e32 v16, v40, v50
	v_mul_f32_e32 v17, v41, v50
	v_cvt_pk_bf16_f32 v16, v16, v17
	v_mul_f32_e32 v17, v42, v50
	v_mul_f32_e32 v18, v43, v50
	v_cvt_pk_bf16_f32 v17, v17, v18
	v_mul_f32_e32 v18, v24, v50
	v_mul_f32_e32 v19, v25, v50
	v_cvt_pk_bf16_f32 v18, v18, v19
	v_mul_f32_e32 v19, v26, v50
	v_mul_f32_e32 v20, v27, v50
	v_cvt_pk_bf16_f32 v19, v19, v20
	global_store_dwordx2 v[48:49], v[16:17], off offset:32
	global_store_dwordx2 v[48:49], v[18:19], off offset:96
	v_mul_f32_e32 v16, v44, v50
	v_mul_f32_e32 v17, v45, v50
	v_cvt_pk_bf16_f32 v16, v16, v17
	v_mul_f32_e32 v17, v46, v50
	v_mul_f32_e32 v18, v47, v50
	v_cvt_pk_bf16_f32 v17, v17, v18
	v_mul_f32_e32 v18, v28, v50
	v_mul_f32_e32 v19, v29, v50
	v_cvt_pk_bf16_f32 v18, v18, v19
	v_mul_f32_e32 v19, v30, v50
	v_mul_f32_e32 v20, v31, v50
	v_cvt_pk_bf16_f32 v19, v19, v20
	global_store_dwordx2 v[48:49], v[16:17], off offset:48
	global_store_dwordx2 v[48:49], v[18:19], off offset:112
	s_cbranch_scc0 .LBB0_732
.LBB0_735:
	s_mov_b32 s99, 0
	v_readlane_b32 s24, v254, 51
	v_mbcnt_lo_u32_b32 v76, -1, 0
	v_mbcnt_hi_u32_b32 v76, -1, v76
	v_readlane_b32 s25, v254, 52
	v_add_u32_e32 v88, s33, v76
	s_andn2_b64 vcc, exec, s[24:25]
	v_readfirstlane_b32 s6, v88
	v_mov_b32_e32 v198, v223
	v_mov_b64_e32 v[210:211], 0x1600
	v_mov_b64_e32 v[214:215], 0x15ff
	v_mov_b64_e32 v[216:217], 0x3ff
	v_mov_b32_e32 v199, 3
	s_cbranch_vccnz .LBB0_754
	v_ashrrev_i32_e32 v90, 3, v88
	v_readlane_b32 s19, v254, 54
	v_readlane_b32 s24, v254, 58
	v_and_b32_e32 v77, 7, v76
	v_add_u32_e32 v0, s19, v90
	v_ashrrev_i32_e32 v1, 31, v0
	v_lshlrev_b64 v[0:1], 10, v[0:1]
	v_readlane_b32 s25, v254, 59
	v_lshlrev_b32_e32 v72, 4, v77
	v_mov_b32_e32 v73, v144
	v_lshl_add_u64 v[0:1], s[24:25], 0, v[0:1]
	v_lshl_add_u64 v[64:65], v[0:1], 0, v[72:73]
	s_mov_b32 s19, 0x10000
	v_add_co_u32_e32 v56, vcc, s19, v64
	s_mov_b32 s19, 0x20000
	s_nop 0
	v_addc_co_u32_e32 v57, vcc, 0, v65, vcc
	v_add_co_u32_e32 v16, vcc, s19, v64
	s_mov_b32 s19, 0x30000
	s_nop 0
	v_addc_co_u32_e32 v17, vcc, 0, v65, vcc
	v_add_co_u32_e32 v20, vcc, s19, v64
	s_mov_b32 s19, 0x40000
	s_nop 0
	v_addc_co_u32_e32 v21, vcc, 0, v65, vcc
	v_add_co_u32_e32 v32, vcc, s19, v64
	s_mov_b32 s19, 0x50000
	s_nop 0
	v_addc_co_u32_e32 v33, vcc, 0, v65, vcc
	v_add_co_u32_e32 v36, vcc, s19, v64
	v_ashrrev_i32_e32 v91, 31, v90
	s_nop 0
	v_addc_co_u32_e32 v37, vcc, 0, v65, vcc
	v_readlane_b32 s24, v254, 62
	v_add_co_u32_e32 v48, vcc, 0x60000, v64
	v_lshlrev_b64 v[74:75], 12, v[90:91]
	v_readlane_b32 s25, v254, 63
	v_addc_co_u32_e32 v49, vcc, 0, v65, vcc
	s_nop 0
	v_lshl_add_u64 v[0:1], s[24:25], 0, v[74:75]
	v_add_co_u32_e32 v52, vcc, 0x70000, v64
	v_lshl_add_u64 v[68:69], v[0:1], 0, v[72:73]
	s_nop 0
	v_addc_co_u32_e32 v53, vcc, 0, v65, vcc
	s_waitcnt lgkmcnt(0)
	global_load_dwordx4 v[0:3], v[64:65], off
	global_load_dwordx4 v[4:7], v[68:69], off
	global_load_dwordx4 v[8:11], v[68:69], off offset:128
	global_load_dwordx4 v[12:15], v[68:69], off offset:256
	s_nop 0
	global_load_dwordx4 v[16:19], v[16:17], off
	s_nop 0
	global_load_dwordx4 v[20:23], v[20:21], off
	s_nop 0
	global_load_dwordx4 v[24:27], v[68:69], off offset:384
	global_load_dwordx4 v[28:31], v[68:69], off offset:512
	s_nop 0
	global_load_dwordx4 v[32:35], v[32:33], off
	s_nop 0
	global_load_dwordx4 v[36:39], v[36:37], off
	s_nop 0
	global_load_dwordx4 v[40:43], v[68:69], off offset:640
	global_load_dwordx4 v[44:47], v[68:69], off offset:768
	s_nop 0
	global_load_dwordx4 v[48:51], v[48:49], off
	s_nop 0
	global_load_dwordx4 v[52:55], v[52:53], off
	s_nop 0
	global_load_dwordx4 v[56:59], v[56:57], off
	s_nop 0
	global_load_dwordx4 v[60:63], v[68:69], off offset:896
	v_readlane_b32 s24, v253, 53
	v_readlane_b32 s25, v253, 54
	s_andn2_b64 vcc, exec, s[24:25]
	s_cbranch_vccnz .LBB0_738
	v_add_co_u32_e32 v64, vcc, 0x80000, v64
	s_nop 1
	v_addc_co_u32_e32 v65, vcc, 0, v65, vcc
	global_load_dwordx4 v[64:67], v[64:65], off
	s_nop 0
	global_load_dwordx4 v[68:71], v[68:69], off offset:1024
	s_branch .LBB0_739

.LBB0_743:
	s_sub_i32 s27, 0xfff, s25
	s_bfe_u32 s26, s27, 0x30004
	s_barrier
	s_cmp_lg_u32 s99, 0
	s_cbranch_scc1 .Lna_tab_done
	s_and_saveexec_b64 s[56:57], s[42:43]
	s_cbranch_execz .LBB0_751
	s_mov_b64 s[60:61], -1
	v_mov_b32_e32 v72, v88
	s_and_saveexec_b64 s[58:59], s[52:53]
	s_cbranch_execz .LBB0_748
	s_mul_i32 s6, s26, 0x1d1
	s_mov_b32 s62, s6
	s_mov_b64 s[60:61], 0
	v_mov_b32_e32 v74, v110
	v_mov_b32_e32 v75, v112
	v_mov_b64_e32 v[72:73], v[88:89]

.LBB0_751:
	s_or_b64 exec, exec, s[56:57]
	s_mov_b32 s99, 1
.Lna_tab_done:
	s_add_i32 s25, s25, s40
	s_cmpk_gt_i32 s25, 0xfff
	s_waitcnt vmcnt(1)
	v_mov_b64_e32 v[76:77], v[80:81]
	s_waitcnt vmcnt(0)
	v_mov_b64_e32 v[72:73], v[84:85]
	s_cselect_b64 s[56:57], -1, 0
	s_cmpk_lt_i32 s25, 0x1000
	v_mov_b64_e32 v[78:79], v[82:83]
	v_mov_b64_e32 v[74:75], v[86:87]
	ds_write_b128 v103, v[0:3] offset:2048
	ds_write_b128 v113, v[4:7]
	ds_write_b128 v103, v[56:59] offset:11264
	ds_write_b128 v113, v[8:11] offset:128
	ds_write_b128 v103, v[16:19] offset:20480
	ds_write_b128 v113, v[12:15] offset:256
	ds_write_b128 v103, v[20:23] offset:29696
	ds_write_b128 v113, v[24:27] offset:384
	ds_write_b128 v103, v[32:35] offset:38912
	ds_write_b128 v113, v[28:31] offset:512
	ds_write_b128 v103, v[36:39] offset:48128
	ds_write_b128 v113, v[40:43] offset:640
	ds_write_b128 v103, v[48:51] offset:57344
	ds_write_b128 v113, v[44:47] offset:768
	ds_write_b128 v104, v[52:55] offset:64512
	ds_write_b128 v113, v[60:63] offset:896
	ds_write_b128 v105, v[64:67]
	ds_write_b128 v113, v[68:71] offset:1024
	s_waitcnt lgkmcnt(0)
	s_barrier
	s_cbranch_scc0 .LBB0_742
	s_sub_i32 s6, 0xfff, s25
	s_bfe_u32 s58, s6, 0x30004
	s_lshr_b32 s28, s6, 7
	s_lshl_b32 s6, s6, 1
	s_and_b32 s59, s6, 30
	v_sub_u32_e64 v0, s59, 4 clamp
	s_lshl_b32 s60, s28, 11
	v_readfirstlane_b32 s6, v0
	s_min_u32 s30, s6, 24
	s_lshl_b32 s6, s30, 6
	s_or_b32 s6, s6, s60
	v_add_u32_e32 v0, s6, v90
	v_ashrrev_i32_e32 v1, 31, v0
	v_readlane_b32 s62, v254, 56
	v_lshlrev_b64 v[0:1], 10, v[0:1]
	v_readlane_b32 s63, v254, 57
	s_lshl_b32 s6, s58, 7
	v_mov_b32_e32 v97, v144
	v_lshl_add_u64 v[0:1], s[62:63], 0, v[0:1]
	v_lshl_add_u64 v[0:1], v[0:1], 0, s[6:7]
	s_lshl_b32 s6, s28, 3
	s_or_b32 s6, s6, s58
	s_lshl_b64 s[28:29], s[6:7], 18
	v_lshl_add_u64 v[64:65], v[0:1], 0, v[96:97]
	v_lshl_add_u64 v[0:1], v[92:93], 0, s[28:29]
	s_lshl_b32 s6, s30, 7
	v_lshl_add_u64 v[0:1], v[0:1], 0, s[6:7]
	s_mov_b32 s6, 0x10000
	v_add_co_u32_e32 v56, vcc, s6, v64
	s_mov_b32 s6, 0x20000
	s_nop 0
	v_addc_co_u32_e32 v57, vcc, 0, v65, vcc
	v_add_co_u32_e32 v16, vcc, s6, v64
	s_mov_b32 s6, 0x30000
	s_nop 0
	v_addc_co_u32_e32 v17, vcc, 0, v65, vcc
	v_add_co_u32_e32 v20, vcc, s6, v64
	s_mov_b32 s6, 0x40000
	s_nop 0
	v_addc_co_u32_e32 v21, vcc, 0, v65, vcc
	v_add_co_u32_e32 v32, vcc, s6, v64
	s_mov_b32 s6, 0x50000
	s_nop 0
	v_addc_co_u32_e32 v33, vcc, 0, v65, vcc
	v_add_co_u32_e32 v36, vcc, s6, v64
	v_lshl_add_u64 v[68:69], v[0:1], 0, v[96:97]
	s_nop 0
	v_addc_co_u32_e32 v37, vcc, 0, v65, vcc
	v_add_co_u32_e32 v48, vcc, 0x60000, v64
	global_load_dwordx4 v[0:3], v[64:65], off
	global_load_dwordx4 v[4:7], v[68:69], off
	v_addc_co_u32_e32 v49, vcc, 0, v65, vcc
	v_add_co_u32_e32 v52, vcc, 0x70000, v64
	global_load_dwordx4 v[8:11], v[68:69], off offset:128
	global_load_dwordx4 v[12:15], v[68:69], off offset:256
	v_addc_co_u32_e32 v53, vcc, 0, v65, vcc
	global_load_dwordx4 v[16:19], v[16:17], off
	s_nop 0
	global_load_dwordx4 v[20:23], v[20:21], off
	s_nop 0
	global_load_dwordx4 v[24:27], v[68:69], off offset:384
	global_load_dwordx4 v[28:31], v[68:69], off offset:512
	s_nop 0
	global_load_dwordx4 v[32:35], v[32:33], off
	s_nop 0
	global_load_dwordx4 v[36:39], v[36:37], off
	s_nop 0
	global_load_dwordx4 v[40:43], v[68:69], off offset:640
	global_load_dwordx4 v[44:47], v[68:69], off offset:768
	s_nop 0
	global_load_dwordx4 v[48:51], v[48:49], off
	s_nop 0
	global_load_dwordx4 v[52:55], v[52:53], off
	s_nop 0
	global_load_dwordx4 v[56:59], v[56:57], off
	s_nop 0
	global_load_dwordx4 v[60:63], v[68:69], off offset:896
	v_sub_u32_e64 v66, s59, 3 clamp
	s_nop 0
	v_readfirstlane_b32 s6, v66
	s_min_u32 s6, s6, 24
	s_sub_i32 s6, s6, s30
	s_add_i32 s6, s6, 8
	s_cmp_lt_i32 s6, 9
	s_cbranch_scc0 .LBB0_740
	v_mov_b32_e32 v145, v144
	v_mov_b32_e32 v146, v144
	v_mov_b32_e32 v147, v144
	v_mov_b64_e32 v[68:69], v[144:145]
	v_mov_b64_e32 v[64:65], v[144:145]
	v_mov_b64_e32 v[70:71], v[146:147]
	v_mov_b64_e32 v[66:67], v[146:147]
	s_branch .LBB0_741

	.amdhsa_kernel _Z8mega_fwd6Params
		.amdhsa_group_segment_fixed_size 0
		.amdhsa_private_segment_fixed_size 0
		.amdhsa_kernarg_size 424
		.amdhsa_user_sgpr_count 2
		.amdhsa_user_sgpr_dispatch_ptr 0
		.amdhsa_user_sgpr_queue_ptr 0
		.amdhsa_user_sgpr_kernarg_segment_ptr 1
		.amdhsa_user_sgpr_dispatch_id 0
		.amdhsa_user_sgpr_kernarg_preload_length 0
		.amdhsa_user_sgpr_kernarg_preload_offset 0
		.amdhsa_user_sgpr_private_segment_size 0
		.amdhsa_uses_dynamic_stack 0
		.amdhsa_enable_private_segment 0
		.amdhsa_system_sgpr_workgroup_id_x 1
		.amdhsa_system_sgpr_workgroup_id_y 0
		.amdhsa_system_sgpr_workgroup_id_z 0
		.amdhsa_system_sgpr_workgroup_info 0
		.amdhsa_system_vgpr_workitem_id 2
		.amdhsa_next_free_vgpr 256
		.amdhsa_next_free_sgpr 102
		.amdhsa_accum_offset 256
		.amdhsa_reserve_vcc 1
		.amdhsa_float_round_mode_32 0
		.amdhsa_float_round_mode_16_64 0
		.amdhsa_float_denorm_mode_32 3
		.amdhsa_float_denorm_mode_16_64 3
		.amdhsa_dx10_clamp 1
		.amdhsa_ieee_mode 1
		.amdhsa_fp16_overflow 0
		.amdhsa_tg_split 0
		.amdhsa_exception_fp_ieee_invalid_op 0
		.amdhsa_exception_fp_denorm_src 0
		.amdhsa_exception_fp_ieee_div_zero 0
		.amdhsa_exception_fp_ieee_overflow 0
		.amdhsa_exception_fp_ieee_underflow 0
		.amdhsa_exception_fp_ieee_inexact 0
		.amdhsa_exception_int_div_zero 0
	.end_amdhsa_kernel

amdhsa.kernels:
  - .agpr_count:     0
    .args:
      - .offset:         0
        .size:           168
        .value_kind:     by_value
      - .offset:         168
        .size:           4
        .value_kind:     hidden_block_count_x
      - .offset:         172
        .size:           4
        .value_kind:     hidden_block_count_y
      - .offset:         176
        .size:           4
        .value_kind:     hidden_block_count_z
      - .offset:         180
        .size:           2
        .value_kind:     hidden_group_size_x
      - .offset:         182
        .size:           2
        .value_kind:     hidden_group_size_y
      - .offset:         184
        .size:           2
        .value_kind:     hidden_group_size_z
      - .offset:         186
        .size:           2
        .value_kind:     hidden_remainder_x
      - .offset:         188
        .size:           2
        .value_kind:     hidden_remainder_y
      - .offset:         190
        .size:           2
        .value_kind:     hidden_remainder_z
      - .offset:         208
        .size:           8
        .value_kind:     hidden_global_offset_x
      - .offset:         216
        .size:           8
        .value_kind:     hidden_global_offset_y
      - .offset:         224
        .size:           8
        .value_kind:     hidden_global_offset_z
      - .offset:         232
        .size:           2
        .value_kind:     hidden_grid_dims
      - .offset:         256
        .size:           8
        .value_kind:     hidden_multigrid_sync_arg
      - .offset:         288
        .size:           4
        .value_kind:     hidden_dynamic_lds_size
    .group_segment_fixed_size: 0
    .kernarg_segment_align: 8
    .kernarg_segment_size: 424
    .language:       OpenCL C
    .language_version:
      - 2
      - 0
    .max_flat_workgroup_size: 512
    .name:           _Z8mega_fwd6Params
    .private_segment_fixed_size: 0
    .sgpr_count:     108
    .sgpr_spill_count: 243
    .symbol:         _Z8mega_fwd6Params.kd
    .uniform_work_group_size: 1
    .uses_dynamic_stack: false
    .vgpr_count:     256
    .vgpr_spill_count: 0
    .wavefront_size: 64
